# v13 plus attention-loop LDS-DMA issue with SGPR base and 32-bit VGPR offset instead of 64-bit VALU address adds
# baseline (speedup 1.0000x reference)
; #define LAS __attribute__((address_space(3)))
; __device__ __forceinline__ void finishSM(f32x16& p0, f32x16& p1, float alpha, float& l_reg, bf16x8& pa0, bf16x8& pa1, bf16x8& pa2, bf16x8& pa3) {
; #pragma unroll
;     for (int r = 0; r < 16; ++r) p1[r] = __builtin_amdgcn_exp2f(p1[r]);
;     float ps = 0;
; #pragma unroll
;     for (int r = 0; r < 16; ++r) ps += p0[r];
; #pragma unroll
;     for (int r = 0; r < 16; ++r) ps += p1[r];
;     { auto rr = __builtin_amdgcn_permlane32_swap(__float_as_uint(ps), __float_as_uint(ps), false, false);
;       ps = __uint_as_float(rr[0]) + __uint_as_float(rr[1]); }
;     l_reg = l_reg * alpha + ps;
;     ...
;     PK4(p0, 0, pa0); PK4(p0, 8, pa1); PK4(p1, 0, pa2); PK4(p1, 8, pa3);
;     ...
; }
; __device__ __forceinline__ void qkt(f32x16& p0, f32x16& p1, const char* Kslot, int r32, int hi, const bf16x8* qr, const LAS f32x4* cp) {
; #pragma unroll
;     for (int g = 0; g < 4; ++g) { const f32x4 c0 = cp[2 * g], c1 = cp[8 + 2 * g];
; #pragma unroll
;         for (int j = 0; j < 4; ++j) { p0[4 * g + j] = c0[j]; p1[4 * g + j] = c1[j]; } }
;     const char* kb[4];
; #pragma unroll
;     for (int dd = 0; dd < 4; ++dd) kb[dd] = Kslot + KSWZ(r32, (dd * 16 + hi * 8) * 2);
; #pragma unroll
;     for (int d0 = 0; d0 < 8; ++d0) { const char* a = kb[d0 & 3] + (d0 >> 2) * 128;
;         bf16x8 b0 = *reinterpret_cast<const bf16x8*>(a);
;         bf16x8 b1 = *reinterpret_cast<const bf16x8*>(a + 32 * 256);
;         p0 = __builtin_amdgcn_mfma_f32_32x32x16_bf16(b0, qr[d0], p0, 0, 0, 0);
;         p1 = __builtin_amdgcn_mfma_f32_32x32x16_bf16(b1, qr[d0], p1, 0, 0, 0); }
.LBB0_521:
	s_add_i32 s3, s71, -1
	s_cmp_lt_u32 s3, s93
	s_cselect_b64 s[88:89], -1, 0
	s_cmp_ge_u32 s3, s93
	s_cselect_b64 s[96:97], -1, 0
	s_and_b64 vcc, exec, s[96:97]
	s_cbranch_vccnz .LBB0_523
	s_add_i32 s3, s70, s72
	s_add_u32 s98, s68, s80
	s_addc_u32 s99, s69, s81
	s_add_i32 m0, s3, 0xc000
	s_add_i32 s3, s3, 0xc400
	global_load_lds_dwordx4 v128, s[98:99]
	s_mov_b32 m0, s3
	s_nop 0
	global_load_lds_dwordx4 v148, s[98:99]
.LBB0_523:
	s_add_i32 s3, s70, s76
	s_add_u32 s100, s68, s84
	s_addc_u32 s101, s69, s85
	s_mov_b32 m0, s3
	s_nop 0
	global_load_lds_dwordx4 v150, s[100:101]
	s_add_i32 m0, s3, 0x400
	s_nop 0
	global_load_lds_dwordx4 v152, s[100:101]
	s_add_i32 s3, s73, 0
	v_add_u32_e32 v218, s3, v193
	ds_read_b128 v[80:83], v217
	ds_read_b128 v[84:87], v217 offset:32
	ds_read_b128 v[64:67], v217 offset:128
	ds_read_b128 v[68:71], v217 offset:160
	ds_read_b128 v[88:91], v217 offset:64
	ds_read_b128 v[72:75], v217 offset:192
	ds_read_b128 v[92:95], v217 offset:96
	ds_read_b128 v[76:79], v217 offset:224
	ds_read_b128 v[238:241], v218 offset:49152
	ds_read_b128 v[242:245], v218 offset:57344
	v_add_u32_e32 v219, s3, v194
	v_add_u32_e32 v220, s3, v195
	s_waitcnt lgkmcnt(0)
	v_mfma_f32_32x32x16_bf16 v[80:95], v[238:241], v[96:99], v[80:95]
	v_add_u32_e32 v237, s3, v196
	v_exp_f32_e32 v173, v173
	v_exp_f32_e32 v176, v176
	v_exp_f32_e32 v177, v177
	v_exp_f32_e32 v178, v178
	v_exp_f32_e32 v179, v179
	v_exp_f32_e32 v246, v165
	v_mfma_f32_32x32x16_bf16 v[64:79], v[242:245], v[96:99], v[64:79]
	ds_read_b128 v[238:241], v219 offset:49152
	ds_read_b128 v[242:245], v219 offset:57344
	s_waitcnt lgkmcnt(0)
	v_mfma_f32_32x32x16_bf16 v[64:79], v[242:245], v[100:103], v[64:79]
	v_mfma_f32_32x32x16_bf16 v[80:95], v[238:241], v[100:103], v[80:95]
	ds_read_b128 v[238:241], v220 offset:49152
	ds_read_b128 v[242:245], v220 offset:57344
	s_waitcnt lgkmcnt(0)
	v_mfma_f32_32x32x16_bf16 v[64:79], v[242:245], v[104:107], v[64:79]
	v_mfma_f32_32x32x16_bf16 v[80:95], v[238:241], v[104:107], v[80:95]
	ds_read_b128 v[238:241], v237 offset:49152
	ds_read_b128 v[242:245], v237 offset:57344
	s_waitcnt lgkmcnt(0)
	v_mfma_f32_32x32x16_bf16 v[64:79], v[242:245], v[108:111], v[64:79]
	v_mfma_f32_32x32x16_bf16 v[80:95], v[238:241], v[108:111], v[80:95]
	v_xor_b32_e32 v249, 0x80, v218
	v_xor_b32_e32 v250, 0x80, v219
	v_xor_b32_e32 v251, 0x80, v220
	v_xor_b32_e32 v252, 0x80, v237
	ds_read_b128 v[238:241], v249 offset:49152
	ds_read_b128 v[242:245], v249 offset:57344
	s_waitcnt lgkmcnt(0)
	v_mfma_f32_32x32x16_bf16 v[64:79], v[242:245], v[112:115], v[64:79]
	v_mfma_f32_32x32x16_bf16 v[80:95], v[238:241], v[112:115], v[80:95]
	ds_read_b128 v[238:241], v250 offset:49152
	ds_read_b128 v[242:245], v250 offset:57344
	s_waitcnt lgkmcnt(0)
	v_mfma_f32_32x32x16_bf16 v[64:79], v[242:245], v[116:119], v[64:79]
	v_mfma_f32_32x32x16_bf16 v[80:95], v[238:241], v[116:119], v[80:95]
	ds_read_b128 v[238:241], v251 offset:49152
	ds_read_b128 v[242:245], v251 offset:57344
	v_exp_f32_e32 v220, v168
	s_waitcnt lgkmcnt(0)
	v_mfma_f32_32x32x16_bf16 v[64:79], v[242:245], v[120:123], v[64:79]
	v_mfma_f32_32x32x16_bf16 v[80:95], v[238:241], v[120:123], v[80:95]
	ds_read_b128 v[238:241], v252 offset:49152
	ds_read_b128 v[242:245], v252 offset:57344
	v_exp_f32_e32 v237, v169
	s_waitcnt lgkmcnt(0)
	v_mfma_f32_32x32x16_bf16 v[64:79], v[242:245], v[124:127], v[64:79]
	v_exp_f32_e32 v245, v164
	v_add_f32_e32 v164, 0, v221
	v_add_f32_e32 v164, v236, v164
	v_add_f32_e32 v164, v233, v164
	v_add_f32_e32 v164, v235, v164
	v_add_f32_e32 v164, v231, v164
	v_add_f32_e32 v164, v234, v164
	v_add_f32_e32 v164, v230, v164
	v_add_f32_e32 v164, v232, v164
	v_add_f32_e32 v164, v227, v164
	v_add_f32_e32 v164, v229, v164
	v_add_f32_e32 v164, v225, v164
	v_add_f32_e32 v164, v228, v164
	v_add_f32_e32 v164, v223, v164
	v_add_f32_e32 v164, v226, v164
	v_mfma_f32_32x32x16_bf16 v[80:95], v[238:241], v[124:127], v[80:95]
	v_exp_f32_e32 v238, v172
	v_add_f32_e32 v164, v222, v164
	v_add_f32_e32 v164, v224, v164
	v_add_f32_e32 v164, v220, v164
	v_add_f32_e32 v164, v237, v164
	v_exp_f32_e32 v239, v166
	v_add_f32_e32 v164, v238, v164
	v_exp_f32_e32 v240, v167
	v_add_f32_e32 v164, v173, v164
	v_exp_f32_e32 v241, v170
	v_add_f32_e32 v164, v176, v164
	v_exp_f32_e32 v242, v171
	v_add_f32_e32 v164, v177, v164
	v_exp_f32_e32 v243, v174
	v_add_f32_e32 v164, v239, v164
	v_exp_f32_e32 v244, v175
	v_add_f32_e32 v164, v240, v164
	v_add_f32_e32 v164, v241, v164
	v_add_f32_e32 v164, v242, v164
	v_add_f32_e32 v164, v243, v164
	v_add_f32_e32 v164, v244, v164
	v_add_f32_e32 v164, v178, v164
	v_add_f32_e32 v164, v179, v164
	v_add_f32_e32 v164, v245, v164
	v_add_f32_e32 v218, v246, v164
	v_mov_b32_e32 v219, v218
	s_nop 1
	v_permlane32_swap_b32_e32 v218, v219
	v_cvt_pk_bf16_f32 v164, v221, v236
	v_cvt_pk_bf16_f32 v165, v233, v235
	v_cvt_pk_bf16_f32 v166, v231, v234
	v_cvt_pk_bf16_f32 v167, v230, v232
	v_cvt_pk_bf16_f32 v168, v227, v229
	v_cvt_pk_bf16_f32 v169, v225, v228
	v_cvt_pk_bf16_f32 v170, v223, v226
	v_cvt_pk_bf16_f32 v171, v222, v224
	v_cvt_pk_bf16_f32 v172, v220, v237
	v_cvt_pk_bf16_f32 v173, v238, v173
	v_cvt_pk_bf16_f32 v174, v176, v177
	v_cvt_pk_bf16_f32 v175, v239, v240
	v_cvt_pk_bf16_f32 v176, v241, v242
	v_cvt_pk_bf16_f32 v177, v243, v244
	v_cvt_pk_bf16_f32 v178, v178, v179
	v_cvt_pk_bf16_f32 v179, v245, v246
	s_nop 0
	v_permlane32_swap_b32_e32 v164, v166
	v_permlane32_swap_b32_e32 v165, v167
	v_permlane32_swap_b32_e32 v168, v170
	v_permlane32_swap_b32_e32 v169, v171
	v_permlane32_swap_b32_e32 v172, v174
	v_permlane32_swap_b32_e32 v173, v175
	v_permlane32_swap_b32_e32 v176, v178
	v_permlane32_swap_b32_e32 v177, v179
	v_add_u32_e32 v236, s2, v192
	s_sub_i32 s2, s92, 64
	s_cmp_le_i32 s2, s91
	s_cbranch_scc0 .Lband_0
; #define SBAR() __builtin_amdgcn_sched_barrier(0)
; #define PV_RD(d0, kh, X) do { constexpr int b_ = v_rd_off(d0, 2 * (kh), 0); TRRD(X##l0, b_); TRRD(X##h0, b_ + 2048); TRRD(X##l1, b_ + 4096); TRRD(X##h1, b_ + 6144); } while (0)
; #define PV_MM(d0, X, PA, PB) do { \
;         o[d0] = __builtin_amdgcn_mfma_f32_32x32x16_bf16(PA, (bf16x8){X##l0[0], X##l0[1], X##l0[2], X##l0[3], X##h0[0], X##h0[1], X##h0[2], X##h0[3]}, o[d0], 0, 0, 0);   \
;         o[d0] = __builtin_amdgcn_mfma_f32_32x32x16_bf16(PB, (bf16x8){X##l1[0], X##l1[1], X##l1[2], X##l1[3], X##h1[0], X##h1[1], X##h1[2], X##h1[3]}, o[d0], 0, 0, 0); } while (0)
; #define PV_W4() do { asm volatile("s_waitcnt lgkmcnt(4)" ::: "memory"); SBAR(); } while (0)
; #define PV_W0() do { asm volatile("s_waitcnt lgkmcnt(0)" ::: "memory"); SBAR(); } while (0)
; __device__ __forceinline__ void partialSM(f32x16& p0, f32x16& p1, float& m_reg, float& mn, float& alpha) {
;     float pmax = p0[0];
; #pragma unroll
;     for (int r = 1; r < 16; ++r) pmax = fmaxf(pmax, p0[r]);
; #pragma unroll
;     for (int r = 0; r < 16; ++r) pmax = fmaxf(pmax, p1[r]);
;     { auto rr = __builtin_amdgcn_permlane32_swap(__float_as_uint(pmax), __float_as_uint(pmax), false, false);
;       pmax = fmaxf(__uint_as_float(rr[0]), __uint_as_float(rr[1])); }
;     if (__builtin_expect(__all((pmax - m_reg) <= THR2), 1)) { mn = m_reg; alpha = 1.f; }
;     else { mn = fmaxf(m_reg, pmax); alpha = __builtin_amdgcn_exp2f(m_reg - mn); m_reg = mn; }
; __device__ __forceinline__ void pv_tile(f32x16* o, int vb0, bf16x8 pa0, bf16x8 pa1, bf16x8 pa2, bf16x8 pa3) {
;     ...
;     s16x4 al0, al1, ah0, ah1, bl0, bl1, bh0, bh1;
;     PV_RD(0, 0, a);
;     PV_RD(0, 1, b); PV_W4(); PV_MM(0, a, pa0, pa1); SBAR();
;     PV_RD(1, 0, a); PV_W4(); PV_MM(0, b, pa2, pa3); SBAR();
;     PV_RD(1, 1, b); PV_W4(); PV_MM(1, a, pa0, pa1); SBAR();
;     PV_RD(2, 0, a); PV_W4(); PV_MM(1, b, pa2, pa3); SBAR();
;     PV_RD(2, 1, b); PV_W4(); PV_MM(2, a, pa0, pa1); SBAR();
;     PV_RD(3, 0, a); PV_W4(); PV_MM(2, b, pa2, pa3); SBAR();
;     PV_RD(3, 1, b); PV_W4(); PV_MM(3, a, pa0, pa1); SBAR();
;     PV_W0(); PV_MM(3, b, pa2, pa3);
	ds_read_b64_tr_b16 v[220:221], v236 offset:0
	ds_read_b64_tr_b16 v[222:223], v236 offset:0x800
	ds_read_b64_tr_b16 v[224:225], v236 offset:0x1000
	ds_read_b64_tr_b16 v[226:227], v236 offset:0x1800
	ds_read_b64_tr_b16 v[228:229], v236 offset:0x2000
	ds_read_b64_tr_b16 v[230:231], v236 offset:0x2800
	ds_read_b64_tr_b16 v[232:233], v236 offset:0x3000
	ds_read_b64_tr_b16 v[234:235], v236 offset:0x3800
	s_waitcnt lgkmcnt(4)
	s_nop 0
	v_mfma_f32_32x32x16_bf16 v[48:63], v[164:167], v[220:223], v[48:63]
	v_max_f32_e32 v253, v81, v81
	v_max_f32_e32 v254, v80, v80
	v_mfma_f32_32x32x16_bf16 v[48:63], v[168:171], v[224:227], v[48:63]
	v_max_f32_e32 v253, v254, v253
	v_max3_f32 v253, v253, v82, v83
	ds_read_b64_tr_b16 v[220:221], v236 offset:0x200
	ds_read_b64_tr_b16 v[222:223], v236 offset:0xa00
	ds_read_b64_tr_b16 v[224:225], v236 offset:0x1200
	ds_read_b64_tr_b16 v[226:227], v236 offset:0x1a00
	s_waitcnt lgkmcnt(4)
	v_mfma_f32_32x32x16_bf16 v[48:63], v[172:175], v[228:231], v[48:63]
	v_max3_f32 v253, v253, v84, v85
	v_max3_f32 v253, v253, v86, v87
	v_mfma_f32_32x32x16_bf16 v[48:63], v[176:179], v[232:235], v[48:63]
	v_max3_f32 v253, v253, v88, v89
	v_max3_f32 v253, v253, v90, v91
	ds_read_b64_tr_b16 v[228:229], v236 offset:0x2200
	ds_read_b64_tr_b16 v[230:231], v236 offset:0x2a00
	ds_read_b64_tr_b16 v[232:233], v236 offset:0x3200
	ds_read_b64_tr_b16 v[234:235], v236 offset:0x3a00
	s_waitcnt lgkmcnt(4)
	v_mfma_f32_32x32x16_bf16 v[32:47], v[164:167], v[220:223], v[32:47]
	v_max3_f32 v253, v253, v92, v93
	v_max3_f32 v253, v253, v94, v95
	v_mfma_f32_32x32x16_bf16 v[32:47], v[168:171], v[224:227], v[32:47]
	v_max3_f32 v253, v253, v64, v65
	v_max3_f32 v253, v253, v66, v67
	ds_read_b64_tr_b16 v[220:221], v236 offset:0x400
	ds_read_b64_tr_b16 v[222:223], v236 offset:0xc00
	ds_read_b64_tr_b16 v[224:225], v236 offset:0x1400
	ds_read_b64_tr_b16 v[226:227], v236 offset:0x1c00
	s_waitcnt lgkmcnt(4)
	v_mfma_f32_32x32x16_bf16 v[32:47], v[172:175], v[228:231], v[32:47]
	v_max3_f32 v253, v253, v68, v69
	v_max3_f32 v253, v253, v70, v71
	v_mfma_f32_32x32x16_bf16 v[32:47], v[176:179], v[232:235], v[32:47]
	v_max3_f32 v253, v253, v72, v73
	v_max3_f32 v253, v253, v74, v75
	ds_read_b64_tr_b16 v[228:229], v236 offset:0x2400
	ds_read_b64_tr_b16 v[230:231], v236 offset:0x2c00
	ds_read_b64_tr_b16 v[232:233], v236 offset:0x3400
	ds_read_b64_tr_b16 v[234:235], v236 offset:0x3c00
	s_waitcnt lgkmcnt(4)
	v_mfma_f32_32x32x16_bf16 v[16:31], v[164:167], v[220:223], v[16:31]
	v_max3_f32 v253, v253, v76, v77
	v_max3_f32 v253, v253, v78, v79
	v_mfma_f32_32x32x16_bf16 v[16:31], v[168:171], v[224:227], v[16:31]
	v_mov_b32_e32 v254, v253
	s_nop 1
	ds_read_b64_tr_b16 v[220:221], v236 offset:0x600
	ds_read_b64_tr_b16 v[222:223], v236 offset:0xe00
	ds_read_b64_tr_b16 v[224:225], v236 offset:0x1600
	ds_read_b64_tr_b16 v[226:227], v236 offset:0x1e00
	s_waitcnt lgkmcnt(4)
	v_mfma_f32_32x32x16_bf16 v[16:31], v[172:175], v[228:231], v[16:31]
	v_permlane32_swap_b32_e32 v253, v254
	v_max_f32_e32 v254, v254, v254
	v_mfma_f32_32x32x16_bf16 v[16:31], v[176:179], v[232:235], v[16:31]
	v_max_f32_e32 v253, v253, v253
	v_max_f32_e32 v253, v253, v254
	ds_read_b64_tr_b16 v[228:229], v236 offset:0x2600
	ds_read_b64_tr_b16 v[230:231], v236 offset:0x2e00
	ds_read_b64_tr_b16 v[232:233], v236 offset:0x3600
	ds_read_b64_tr_b16 v[234:235], v236 offset:0x3e00
	s_waitcnt lgkmcnt(4)
	v_mfma_f32_32x32x16_bf16 v[0:15], v[164:167], v[220:223], v[0:15]
	v_sub_f32_e32 v254, v253, v154
	v_cmp_ge_f32_e32 vcc, s33, v254
	v_mfma_f32_32x32x16_bf16 v[0:15], v[168:171], v[224:227], v[0:15]
	v_max_f32_e32 v254, v154, v154
	v_max_f32_e32 v253, v254, v253
	s_waitcnt lgkmcnt(0)
	v_mfma_f32_32x32x16_bf16 v[0:15], v[172:175], v[228:231], v[0:15]
	v_sub_f32_e32 v254, v154, v253
	v_exp_f32_e32 v254, v254
	v_mfma_f32_32x32x16_bf16 v[0:15], v[176:179], v[232:235], v[0:15]
	v_mov_b32_e32 v164, v253
	v_mov_b32_e32 v165, v254
	s_branch .Lmaxtail_0

; #define SBAR() __builtin_amdgcn_sched_barrier(0)
; #define WAITV_BAR(N) asm volatile("s_waitcnt vmcnt(" #N ") lgkmcnt(0)\n\ts_barrier" ::: "memory")
; #define DMA_K(t, slot) do { _Pragma("unroll") for (int i_ = 0; i_ < 2; ++i_) __builtin_amdgcn_global_load_lds((const unsigned*)((const char*)Kh + (size_t)(t) * (KVBLK * D * 2) + dof.k[i_]), \
;         (LAS unsigned*)((LAS unsigned char*)lds3 + OFF_K + (slot) + (wid * 2 + i_) * 1024), 16, 0, 0); } while (0)
; #define DMA_V(t, slot) do { _Pragma("unroll") for (int i_ = 0; i_ < 2; ++i_) __builtin_amdgcn_global_load_lds((const unsigned*)((const char*)Vh + (size_t)(t) * (KVBLK * D * 2) + dof.v[i_]), \
;         (LAS unsigned*)((LAS unsigned char*)lds3 + (slot) + (wid * 2 + i_) * 1024), 16, 0, 0); } while (0)
; #define ROT() do { s_prev = s_cur; s_cur = s_next; s_next = s_nn; s_nn = (s_nn == (NSLOT - 1) * SLOT) ? 0 : s_nn + SLOT; } while (0)
; __device__ __forceinline__ void fox_block(const BlockRef& cur, const BlockRef& nxt, char* lds, Seam& S, const int tid) {
;     ...
;     f32x16 pA0, pA1, pB0, pB1; float mnA, mnB, alA, alB; bf16x8 pa0, pa1, pa2, pa3;
;     int s_prev = 0, s_cur = 0, s_next = SLOT, s_nn = 2 * SLOT;
;     SBAR(); DMA_K(2, s_nn); DMA_V(1, s_next); SBAR();
;     qkt(pA0, pA1, K_lds + s_cur, r32, hi, S.qr, CTP(0));
;     mask_meta(pA0, pA1); partialSM(pA0, pA1, m_reg, mnA, alA);
;     SBAR(); WAITV_BAR(4);
;     ROT();
.LBB0_533:
	s_add_i32 s4, s72, 0x4000
	s_cmpk_lg_u32 s72, 0x8000
	s_cselect_b32 s90, s4, 0
	s_cmp_ge_u32 s71, s93
	s_cselect_b64 s[86:87], -1, 0
	s_and_b64 vcc, exec, s[86:87]
	s_cbranch_vccnz .LBB0_535
	s_add_i32 s4, s70, s90
	s_add_u32 s98, s68, s74
	s_addc_u32 s99, s69, s75
	s_add_i32 m0, s4, 0xc000
	s_add_i32 s4, s4, 0xc400
	global_load_lds_dwordx4 v128, s[98:99]
	s_mov_b32 m0, s4
	s_nop 0
	global_load_lds_dwordx4 v148, s[98:99]
.LBB0_535:
	s_andn2_b64 vcc, exec, s[88:89]
	s_cbranch_vccnz .LBB0_537
	s_add_i32 s4, s70, s72
	s_add_u32 s100, s68, s94
	s_addc_u32 s101, s69, s95
	s_add_i32 s5, s4, 0x400
	s_mov_b32 m0, s4
	s_nop 0
	global_load_lds_dwordx4 v150, s[100:101]
	s_mov_b32 m0, s5
	s_nop 0
	global_load_lds_dwordx4 v152, s[100:101]

; #define LAS __attribute__((address_space(3)))
; __device__ __forceinline__ void finishSM(f32x16& p0, f32x16& p1, float alpha, float& l_reg, bf16x8& pa0, bf16x8& pa1, bf16x8& pa2, bf16x8& pa3) {
; #pragma unroll
;     for (int r = 0; r < 16; ++r) p1[r] = __builtin_amdgcn_exp2f(p1[r]);
;     float ps = 0;
; #pragma unroll
;     for (int r = 0; r < 16; ++r) ps += p0[r];
; #pragma unroll
;     for (int r = 0; r < 16; ++r) ps += p1[r];
;     { auto rr = __builtin_amdgcn_permlane32_swap(__float_as_uint(ps), __float_as_uint(ps), false, false);
;       ps = __uint_as_float(rr[0]) + __uint_as_float(rr[1]); }
;     l_reg = l_reg * alpha + ps;
;     ...
;     PK4(p0, 0, pa0); PK4(p0, 8, pa1); PK4(p1, 0, pa2); PK4(p1, 8, pa3);
;     ...
; }
; __device__ __forceinline__ void qkt(f32x16& p0, f32x16& p1, const char* Kslot, int r32, int hi, const bf16x8* qr, const LAS f32x4* cp) {
; #pragma unroll
;     for (int g = 0; g < 4; ++g) { const f32x4 c0 = cp[2 * g], c1 = cp[8 + 2 * g];
; #pragma unroll
;         for (int j = 0; j < 4; ++j) { p0[4 * g + j] = c0[j]; p1[4 * g + j] = c1[j]; } }
;     const char* kb[4];
; #pragma unroll
;     for (int dd = 0; dd < 4; ++dd) kb[dd] = Kslot + KSWZ(r32, (dd * 16 + hi * 8) * 2);
; #pragma unroll
;     for (int d0 = 0; d0 < 8; ++d0) { const char* a = kb[d0 & 3] + (d0 >> 2) * 128;
;         bf16x8 b0 = *reinterpret_cast<const bf16x8*>(a);
;         bf16x8 b1 = *reinterpret_cast<const bf16x8*>(a + 32 * 256);
;         p0 = __builtin_amdgcn_mfma_f32_32x32x16_bf16(b0, qr[d0], p0, 0, 0, 0);
;         p1 = __builtin_amdgcn_mfma_f32_32x32x16_bf16(b1, qr[d0], p1, 0, 0, 0); }
.LBB0_556:
	s_add_i32 s3, s87, -1
	s_cmp_lt_u32 s3, s89
	s_cselect_b64 s[78:79], -1, 0
	s_cmp_ge_u32 s3, s89
	s_cselect_b64 s[66:67], -1, 0
	s_and_b64 vcc, exec, s[66:67]
	s_cbranch_vccnz .LBB0_558
	s_add_i32 s3, s86, s72
	s_add_u32 s98, s82, s80
	s_addc_u32 s99, s83, s81
	s_add_i32 m0, s3, 0xc000
	s_add_i32 s3, s3, 0xc400
	global_load_lds_dwordx4 v128, s[98:99]
	s_mov_b32 m0, s3
	s_nop 0
	global_load_lds_dwordx4 v138, s[98:99]
.LBB0_558:
	s_add_i32 s3, s86, s90
	s_add_u32 s100, s82, s84
	s_addc_u32 s101, s83, s85
	s_mov_b32 m0, s3
	s_nop 0
	global_load_lds_dwordx4 v140, s[100:101]
	s_add_i32 m0, s3, 0x400
	s_nop 0
	global_load_lds_dwordx4 v142, s[100:101]
	s_add_i32 s3, s73, 0
	v_add_u32_e32 v175, s3, v193
	ds_read_b128 v[80:83], v197
	ds_read_b128 v[84:87], v197 offset:32
	ds_read_b128 v[64:67], v197 offset:128
	ds_read_b128 v[68:71], v197 offset:160
	ds_read_b128 v[88:91], v197 offset:64
	ds_read_b128 v[72:75], v197 offset:192
	ds_read_b128 v[92:95], v197 offset:96
	ds_read_b128 v[76:79], v197 offset:224
	ds_read_b128 v[212:215], v175 offset:49152
	ds_read_b128 v[216:219], v175 offset:57344
	v_add_u32_e32 v176, s3, v194
	v_add_u32_e32 v177, s3, v195
	s_waitcnt lgkmcnt(0)
	v_mfma_f32_32x32x16_bf16 v[80:95], v[212:215], v[96:99], v[80:95]
	v_add_u32_e32 v220, s3, v196
	v_exp_f32_e32 v163, v163
	v_exp_f32_e32 v166, v166
	v_exp_f32_e32 v167, v167
	v_exp_f32_e32 v168, v168
	v_exp_f32_e32 v169, v169
	v_exp_f32_e32 v221, v155
	v_mfma_f32_32x32x16_bf16 v[64:79], v[216:219], v[96:99], v[64:79]
	ds_read_b128 v[212:215], v176 offset:49152
	ds_read_b128 v[216:219], v176 offset:57344
	s_waitcnt lgkmcnt(0)
	v_mfma_f32_32x32x16_bf16 v[80:95], v[212:215], v[100:103], v[80:95]
	v_mfma_f32_32x32x16_bf16 v[64:79], v[216:219], v[100:103], v[64:79]
	ds_read_b128 v[212:215], v177 offset:49152
	ds_read_b128 v[216:219], v177 offset:57344
	s_waitcnt lgkmcnt(0)
	v_mfma_f32_32x32x16_bf16 v[80:95], v[212:215], v[104:107], v[80:95]
	v_mfma_f32_32x32x16_bf16 v[64:79], v[216:219], v[104:107], v[64:79]
	ds_read_b128 v[212:215], v220 offset:49152
	ds_read_b128 v[216:219], v220 offset:57344
	s_waitcnt lgkmcnt(0)
	v_mfma_f32_32x32x16_bf16 v[80:95], v[212:215], v[108:111], v[80:95]
	v_mfma_f32_32x32x16_bf16 v[64:79], v[216:219], v[108:111], v[64:79]
	v_xor_b32_e32 v249, 0x80, v175
	v_xor_b32_e32 v250, 0x80, v176
	v_xor_b32_e32 v251, 0x80, v177
	v_xor_b32_e32 v252, 0x80, v220
	ds_read_b128 v[212:215], v249 offset:49152
	ds_read_b128 v[216:219], v249 offset:57344
	s_waitcnt lgkmcnt(0)
	v_mfma_f32_32x32x16_bf16 v[80:95], v[212:215], v[112:115], v[80:95]
	v_mfma_f32_32x32x16_bf16 v[64:79], v[216:219], v[112:115], v[64:79]
	ds_read_b128 v[212:215], v250 offset:49152
	ds_read_b128 v[216:219], v250 offset:57344
	s_waitcnt lgkmcnt(0)
	v_mfma_f32_32x32x16_bf16 v[80:95], v[212:215], v[116:119], v[80:95]
	v_mfma_f32_32x32x16_bf16 v[64:79], v[216:219], v[116:119], v[64:79]
	ds_read_b128 v[212:215], v251 offset:49152
	ds_read_b128 v[216:219], v251 offset:57344
	v_exp_f32_e32 v177, v158
	s_waitcnt lgkmcnt(0)
	v_mfma_f32_32x32x16_bf16 v[80:95], v[212:215], v[120:123], v[80:95]
	v_mfma_f32_32x32x16_bf16 v[64:79], v[216:219], v[120:123], v[64:79]
	ds_read_b128 v[212:215], v252 offset:49152
	ds_read_b128 v[216:219], v252 offset:57344
	v_exp_f32_e32 v220, v154
	v_add_f32_e32 v154, 0, v178
	v_add_f32_e32 v154, v211, v154
	v_add_f32_e32 v154, v208, v154
	v_add_f32_e32 v154, v210, v154
	v_add_f32_e32 v154, v206, v154
	v_add_f32_e32 v154, v209, v154
	v_add_f32_e32 v154, v205, v154
	v_add_f32_e32 v154, v207, v154
	v_add_f32_e32 v154, v202, v154
	v_add_f32_e32 v154, v204, v154
	v_add_f32_e32 v154, v200, v154
	v_add_f32_e32 v154, v203, v154
	v_add_f32_e32 v154, v198, v154
	s_waitcnt lgkmcnt(0)
	v_mfma_f32_32x32x16_bf16 v[80:95], v[212:215], v[124:127], v[80:95]
	v_exp_f32_e32 v212, v159
	v_add_f32_e32 v154, v201, v154
	v_exp_f32_e32 v213, v162
	v_add_f32_e32 v154, v179, v154
	v_add_f32_e32 v154, v199, v154
	v_add_f32_e32 v154, v177, v154
	v_add_f32_e32 v154, v212, v154
	v_exp_f32_e32 v214, v156
	v_add_f32_e32 v154, v213, v154
	v_exp_f32_e32 v215, v157
	v_add_f32_e32 v154, v163, v154
	v_mfma_f32_32x32x16_bf16 v[64:79], v[216:219], v[124:127], v[64:79]
	v_exp_f32_e32 v216, v160
	v_add_f32_e32 v154, v166, v154
	v_exp_f32_e32 v217, v161
	v_add_f32_e32 v154, v167, v154
	v_exp_f32_e32 v218, v164
	v_add_f32_e32 v154, v214, v154
	v_exp_f32_e32 v219, v165
	v_add_f32_e32 v154, v215, v154
	v_add_f32_e32 v154, v216, v154
	v_add_f32_e32 v154, v217, v154
	v_add_f32_e32 v154, v218, v154
	v_add_f32_e32 v154, v219, v154
	v_add_f32_e32 v154, v168, v154
	v_add_f32_e32 v154, v169, v154
	v_add_f32_e32 v154, v220, v154
	v_add_f32_e32 v175, v221, v154
	v_mov_b32_e32 v176, v175
	s_nop 1
	v_permlane32_swap_b32_e32 v175, v176
	v_cvt_pk_bf16_f32 v154, v178, v211
	v_cvt_pk_bf16_f32 v155, v208, v210
	v_cvt_pk_bf16_f32 v156, v206, v209
	v_cvt_pk_bf16_f32 v157, v205, v207
	v_cvt_pk_bf16_f32 v158, v202, v204
	v_cvt_pk_bf16_f32 v159, v200, v203
	v_cvt_pk_bf16_f32 v160, v198, v201
	v_cvt_pk_bf16_f32 v161, v179, v199
	v_cvt_pk_bf16_f32 v162, v177, v212
	v_cvt_pk_bf16_f32 v163, v213, v163
	v_cvt_pk_bf16_f32 v164, v166, v167
	v_cvt_pk_bf16_f32 v165, v214, v215
	v_cvt_pk_bf16_f32 v166, v216, v217
	v_cvt_pk_bf16_f32 v167, v218, v219
	v_cvt_pk_bf16_f32 v168, v168, v169
	v_cvt_pk_bf16_f32 v169, v220, v221
	s_nop 0
	v_permlane32_swap_b32_e32 v154, v156
	v_permlane32_swap_b32_e32 v155, v157
	v_permlane32_swap_b32_e32 v158, v160
	v_permlane32_swap_b32_e32 v159, v161
	v_permlane32_swap_b32_e32 v162, v164
	v_permlane32_swap_b32_e32 v163, v165
	v_permlane32_swap_b32_e32 v166, v168
	v_permlane32_swap_b32_e32 v167, v169
	v_add_u32_e32 v177, s2, v192
	s_sub_i32 s2, s91, 64
	s_cmp_le_i32 s2, s88
	s_cbranch_scc0 .Lband_2
; #define SBAR() __builtin_amdgcn_sched_barrier(0)
; #define PV_RD(d0, kh, X) do { constexpr int b_ = v_rd_off(d0, 2 * (kh), 0); TRRD(X##l0, b_); TRRD(X##h0, b_ + 2048); TRRD(X##l1, b_ + 4096); TRRD(X##h1, b_ + 6144); } while (0)
; #define PV_MM(d0, X, PA, PB) do { \
;         o[d0] = __builtin_amdgcn_mfma_f32_32x32x16_bf16(PA, (bf16x8){X##l0[0], X##l0[1], X##l0[2], X##l0[3], X##h0[0], X##h0[1], X##h0[2], X##h0[3]}, o[d0], 0, 0, 0);   \
;         o[d0] = __builtin_amdgcn_mfma_f32_32x32x16_bf16(PB, (bf16x8){X##l1[0], X##l1[1], X##l1[2], X##l1[3], X##h1[0], X##h1[1], X##h1[2], X##h1[3]}, o[d0], 0, 0, 0); } while (0)
; #define PV_W4() do { asm volatile("s_waitcnt lgkmcnt(4)" ::: "memory"); SBAR(); } while (0)
; #define PV_W0() do { asm volatile("s_waitcnt lgkmcnt(0)" ::: "memory"); SBAR(); } while (0)
; __device__ __forceinline__ void partialSM(f32x16& p0, f32x16& p1, float& m_reg, float& mn, float& alpha) {
;     float pmax = p0[0];
; #pragma unroll
;     for (int r = 1; r < 16; ++r) pmax = fmaxf(pmax, p0[r]);
; #pragma unroll
;     for (int r = 0; r < 16; ++r) pmax = fmaxf(pmax, p1[r]);
;     { auto rr = __builtin_amdgcn_permlane32_swap(__float_as_uint(pmax), __float_as_uint(pmax), false, false);
;       pmax = fmaxf(__uint_as_float(rr[0]), __uint_as_float(rr[1])); }
;     if (__builtin_expect(__all((pmax - m_reg) <= THR2), 1)) { mn = m_reg; alpha = 1.f; }
;     else { mn = fmaxf(m_reg, pmax); alpha = __builtin_amdgcn_exp2f(m_reg - mn); m_reg = mn; }
; __device__ __forceinline__ void pv_tile(f32x16* o, int vb0, bf16x8 pa0, bf16x8 pa1, bf16x8 pa2, bf16x8 pa3) {
;     ...
;     s16x4 al0, al1, ah0, ah1, bl0, bl1, bh0, bh1;
;     PV_RD(0, 0, a);
;     PV_RD(0, 1, b); PV_W4(); PV_MM(0, a, pa0, pa1); SBAR();
;     PV_RD(1, 0, a); PV_W4(); PV_MM(0, b, pa2, pa3); SBAR();
;     PV_RD(1, 1, b); PV_W4(); PV_MM(1, a, pa0, pa1); SBAR();
;     PV_RD(2, 0, a); PV_W4(); PV_MM(1, b, pa2, pa3); SBAR();
;     PV_RD(2, 1, b); PV_W4(); PV_MM(2, a, pa0, pa1); SBAR();
;     PV_RD(3, 0, a); PV_W4(); PV_MM(2, b, pa2, pa3); SBAR();
;     PV_RD(3, 1, b); PV_W4(); PV_MM(3, a, pa0, pa1); SBAR();
;     PV_W0(); PV_MM(3, b, pa2, pa3);
	ds_read_b64_tr_b16 v[198:199], v177 offset:0
	ds_read_b64_tr_b16 v[200:201], v177 offset:0x800
	ds_read_b64_tr_b16 v[202:203], v177 offset:0x1000
	ds_read_b64_tr_b16 v[204:205], v177 offset:0x1800
	ds_read_b64_tr_b16 v[206:207], v177 offset:0x2000
	ds_read_b64_tr_b16 v[208:209], v177 offset:0x2800
	ds_read_b64_tr_b16 v[210:211], v177 offset:0x3000
	ds_read_b64_tr_b16 v[212:213], v177 offset:0x3800
	s_waitcnt lgkmcnt(4)
	s_nop 0
	v_mfma_f32_32x32x16_bf16 v[48:63], v[154:157], v[198:201], v[48:63]
	v_max_f32_e32 v253, v81, v81
	v_max_f32_e32 v254, v80, v80
	v_mfma_f32_32x32x16_bf16 v[48:63], v[158:161], v[202:205], v[48:63]
	v_max_f32_e32 v253, v254, v253
	v_max3_f32 v253, v253, v82, v83
	ds_read_b64_tr_b16 v[198:199], v177 offset:0x200
	ds_read_b64_tr_b16 v[200:201], v177 offset:0xa00
	ds_read_b64_tr_b16 v[202:203], v177 offset:0x1200
	ds_read_b64_tr_b16 v[204:205], v177 offset:0x1a00
	s_waitcnt lgkmcnt(4)
	v_mfma_f32_32x32x16_bf16 v[48:63], v[162:165], v[206:209], v[48:63]
	v_max3_f32 v253, v253, v84, v85
	v_max3_f32 v253, v253, v86, v87
	v_mfma_f32_32x32x16_bf16 v[48:63], v[166:169], v[210:213], v[48:63]
	v_max3_f32 v253, v253, v88, v89
	v_max3_f32 v253, v253, v90, v91
	ds_read_b64_tr_b16 v[206:207], v177 offset:0x2200
	ds_read_b64_tr_b16 v[208:209], v177 offset:0x2a00
	ds_read_b64_tr_b16 v[210:211], v177 offset:0x3200
	ds_read_b64_tr_b16 v[212:213], v177 offset:0x3a00
	s_waitcnt lgkmcnt(4)
	v_mfma_f32_32x32x16_bf16 v[32:47], v[154:157], v[198:201], v[32:47]
	v_max3_f32 v253, v253, v92, v93
	v_max3_f32 v253, v253, v94, v95
	v_mfma_f32_32x32x16_bf16 v[32:47], v[158:161], v[202:205], v[32:47]
	v_max3_f32 v253, v253, v64, v65
	v_max3_f32 v253, v253, v66, v67
	ds_read_b64_tr_b16 v[198:199], v177 offset:0x400
	ds_read_b64_tr_b16 v[200:201], v177 offset:0xc00
	ds_read_b64_tr_b16 v[202:203], v177 offset:0x1400
	ds_read_b64_tr_b16 v[204:205], v177 offset:0x1c00
	s_waitcnt lgkmcnt(4)
	v_mfma_f32_32x32x16_bf16 v[32:47], v[162:165], v[206:209], v[32:47]
	v_max3_f32 v253, v253, v68, v69
	v_max3_f32 v253, v253, v70, v71
	v_mfma_f32_32x32x16_bf16 v[32:47], v[166:169], v[210:213], v[32:47]
	v_max3_f32 v253, v253, v72, v73
	v_max3_f32 v253, v253, v74, v75
	ds_read_b64_tr_b16 v[206:207], v177 offset:0x2400
	ds_read_b64_tr_b16 v[208:209], v177 offset:0x2c00
	ds_read_b64_tr_b16 v[210:211], v177 offset:0x3400
	ds_read_b64_tr_b16 v[212:213], v177 offset:0x3c00
	s_waitcnt lgkmcnt(4)
	v_mfma_f32_32x32x16_bf16 v[16:31], v[154:157], v[198:201], v[16:31]
	v_max3_f32 v253, v253, v76, v77
	v_max3_f32 v253, v253, v78, v79
	v_mfma_f32_32x32x16_bf16 v[16:31], v[158:161], v[202:205], v[16:31]
	v_mov_b32_e32 v254, v253
	s_nop 1
	ds_read_b64_tr_b16 v[198:199], v177 offset:0x600
	ds_read_b64_tr_b16 v[200:201], v177 offset:0xe00
	ds_read_b64_tr_b16 v[202:203], v177 offset:0x1600
	ds_read_b64_tr_b16 v[204:205], v177 offset:0x1e00
	s_waitcnt lgkmcnt(4)
	v_mfma_f32_32x32x16_bf16 v[16:31], v[162:165], v[206:209], v[16:31]
	v_permlane32_swap_b32_e32 v253, v254
	v_max_f32_e32 v254, v254, v254
	v_mfma_f32_32x32x16_bf16 v[16:31], v[166:169], v[210:213], v[16:31]
	v_max_f32_e32 v253, v253, v253
	v_max_f32_e32 v253, v253, v254
	ds_read_b64_tr_b16 v[206:207], v177 offset:0x2600
	ds_read_b64_tr_b16 v[208:209], v177 offset:0x2e00
	ds_read_b64_tr_b16 v[210:211], v177 offset:0x3600
	ds_read_b64_tr_b16 v[212:213], v177 offset:0x3e00
	s_waitcnt lgkmcnt(4)
	v_mfma_f32_32x32x16_bf16 v[0:15], v[154:157], v[198:201], v[0:15]
	v_sub_f32_e32 v254, v253, v144
	v_cmp_ge_f32_e32 vcc, s33, v254
	v_mfma_f32_32x32x16_bf16 v[0:15], v[158:161], v[202:205], v[0:15]
	v_max_f32_e32 v254, v144, v144
	v_max_f32_e32 v253, v254, v253
	s_waitcnt lgkmcnt(0)
	v_mfma_f32_32x32x16_bf16 v[0:15], v[162:165], v[206:209], v[0:15]
	v_sub_f32_e32 v254, v144, v253
	v_exp_f32_e32 v254, v254
	v_mfma_f32_32x32x16_bf16 v[0:15], v[166:169], v[210:213], v[0:15]
	v_mov_b32_e32 v154, v253
	v_mov_b32_e32 v155, v254
	s_branch .Lmaxtail_2

; #define SBAR() __builtin_amdgcn_sched_barrier(0)
; #define WAITV_BAR(N) asm volatile("s_waitcnt vmcnt(" #N ") lgkmcnt(0)\n\ts_barrier" ::: "memory")
; #define DMA_K(t, slot) do { _Pragma("unroll") for (int i_ = 0; i_ < 2; ++i_) __builtin_amdgcn_global_load_lds((const unsigned*)((const char*)Kh + (size_t)(t) * (KVBLK * D * 2) + dof.k[i_]), \
;         (LAS unsigned*)((LAS unsigned char*)lds3 + OFF_K + (slot) + (wid * 2 + i_) * 1024), 16, 0, 0); } while (0)
; #define DMA_V(t, slot) do { _Pragma("unroll") for (int i_ = 0; i_ < 2; ++i_) __builtin_amdgcn_global_load_lds((const unsigned*)((const char*)Vh + (size_t)(t) * (KVBLK * D * 2) + dof.v[i_]), \
;         (LAS unsigned*)((LAS unsigned char*)lds3 + (slot) + (wid * 2 + i_) * 1024), 16, 0, 0); } while (0)
; #define ROT() do { s_prev = s_cur; s_cur = s_next; s_next = s_nn; s_nn = (s_nn == (NSLOT - 1) * SLOT) ? 0 : s_nn + SLOT; } while (0)
; __device__ __forceinline__ void fox_block(const BlockRef& cur, const BlockRef& nxt, char* lds, Seam& S, const int tid) {
;     ...
;     f32x16 pA0, pA1, pB0, pB1; float mnA, mnB, alA, alB; bf16x8 pa0, pa1, pa2, pa3;
;     int s_prev = 0, s_cur = 0, s_next = SLOT, s_nn = 2 * SLOT;
;     SBAR(); DMA_K(2, s_nn); DMA_V(1, s_next); SBAR();
;     qkt(pA0, pA1, K_lds + s_cur, r32, hi, S.qr, CTP(0));
;     mask_meta(pA0, pA1); partialSM(pA0, pA1, m_reg, mnA, alA);
;     SBAR(); WAITV_BAR(4);
;     ROT();
.LBB0_568:
	s_add_i32 s4, s72, 0x4000
	s_cmpk_lg_u32 s72, 0x8000
	s_cselect_b32 s92, s4, 0
	s_cmp_ge_u32 s87, s89
	s_cselect_b64 s[76:77], -1, 0
	s_and_b64 vcc, exec, s[76:77]
	s_cbranch_vccnz .LBB0_570
	s_add_i32 s4, s86, s92
	s_add_u32 s98, s82, s74
	s_addc_u32 s99, s83, s75
	s_add_i32 m0, s4, 0xc000
	s_add_i32 s4, s4, 0xc400
	global_load_lds_dwordx4 v128, s[98:99]
	s_mov_b32 m0, s4
	s_nop 0
	global_load_lds_dwordx4 v138, s[98:99]
.LBB0_570:
	s_andn2_b64 vcc, exec, s[78:79]
	s_cbranch_vccnz .LBB0_572
	s_add_i32 s4, s86, s72
	s_add_u32 s100, s82, s94
	s_addc_u32 s101, s83, s95
	s_add_i32 s5, s4, 0x400
	s_mov_b32 m0, s4
	s_nop 0
	global_load_lds_dwordx4 v140, s[100:101]
	s_mov_b32 m0, s5
	s_nop 0
	global_load_lds_dwordx4 v142, s[100:101]
